# P2 rwkv_prep staging loop: merged prev/cur loads under one wait, shift_mix loads hoisted out of loop
# speedup vs baseline: 1.0150x; 1.0057x over previous
; DI f32x4 shifted4(const Params& p, int l, int t, int col) {
;     ...
;   f32x4 m0 = ld4(p.in[I_MIX] + ((size_t)l * 2 + 0) * 2176 + col);
;   f32x4 m1 = ld4(p.in[I_MIX] + ((size_t)l * 2 + 1) * 2176 + col);
; DI void rwkv_prep_tile(const int wv, const Params& p, int l, int mtile, int h, char* s0, char* s1, char* s2) {
;   int tid = opaque_tid(wv);
;   const u16* z = (const u16*)(p.ws + WS_Z);
;   char* sAw = s0;
;   char* sAa = s1;
;   char* sBw = s2;
;   char* sBa = s2 + 64 * LDA;
;   const int t0 = mtile * 128;
;   __syncthreads();
;   {
;     const int c8 = (tid & 15) * 8;
; #pragma unroll 1
;     for (int i = 0; i < 8; ++i) {
;       const int row = (tid >> 4) + 16 * i;
;       f32x4 a = shifted4(p, l, t0 + row, C_WL + c8);
;       f32x4 b = shifted4(p, l, t0 + row, C_WL + c8 + 4);
.LBB0_408:
	s_ashr_i32 s2, s21, 31
	s_lshr_b32 s2, s2, 26
	s_add_i32 s2, s21, s2
	s_ashr_i32 s8, s2, 6
	s_lshl_b32 s28, s8, 3
	s_sub_i32 s3, s58, s28
	s_min_i32 s83, s3, 8
	s_abs_i32 s3, s83
	v_cvt_f32_u32_e32 v0, s3
	s_sub_i32 s38, 0, s3
	s_andn2_b32 s2, s2, 63
	s_sub_i32 s81, s21, s2
	v_rcp_iflag_f32_e32 v0, v0
	s_abs_i32 s2, s81
	s_xor_b32 s9, s81, s83
	s_ashr_i32 s9, s9, 31
	v_mul_f32_e32 v0, 0x4f7ffffe, v0
	v_cvt_u32_f32_e32 v0, v0
	s_waitcnt vmcnt(0)
	v_mbcnt_lo_u32_b32 v4, -1, 0
	v_mbcnt_hi_u32_b32 v4, -1, v4
	s_mul_i32 s8, s8, 56
	v_or_b32_e32 v46, s55, v4
	v_readfirstlane_b32 s39, v0
	s_mul_i32 s38, s38, s39
	s_mul_hi_u32 s38, s39, s38
	s_add_i32 s39, s39, s38
	s_mul_hi_u32 s38, s2, s39
	s_mul_i32 s39, s38, s3
	s_sub_i32 s2, s2, s39
	s_add_i32 s40, s38, 1
	s_sub_i32 s39, s2, s3
	s_cmp_ge_u32 s2, s3
	s_cselect_b32 s38, s40, s38
	s_cselect_b32 s2, s39, s2
	s_add_i32 s39, s38, 1
	s_cmp_ge_u32 s2, s3
	v_lshlrev_b32_e32 v0, 3, v4
	s_cselect_b32 s2, s39, s38
	v_and_b32_e32 v0, 0x78, v0
	s_xor_b32 s2, s2, s9
	v_ashrrev_i32_e32 v2, 4, v46
	v_or_b32_e32 v3, 0x800, v0
	v_or_b32_e32 v5, 0x804, v0
	v_cmp_gt_u32_e32 vcc, 64, v0
	v_lshlrev_b32_e32 v0, 4, v4
	s_sub_i32 s63, s2, s9
	v_and_b32_e32 v18, 0x70, v0
	v_and_b32_e32 v19, 15, v2
	s_mul_i32 s83, s83, s63
	v_lshlrev_b32_e32 v0, 1, v3
	v_mad_u64_u32 v[36:37], s[2:3], v2, s68, v[18:19]
	v_lshl_add_u64 v[20:21], s[42:43], 0, v[0:1]
	v_lshlrev_b32_e32 v0, 2, v3
	s_sub_i32 s2, s20, s83
	v_lshl_add_u64 v[22:23], s[6:7], 0, v[0:1]
	v_lshl_add_u64 v[24:25], s[44:45], 0, v[0:1]
	v_lshl_add_u64 v[26:27], s[46:47], 0, v[0:1]
	v_lshlrev_b32_e32 v0, 1, v5
	s_sub_i32 s2, s2, s8
	v_lshl_add_u64 v[28:29], s[42:43], 0, v[0:1]
	v_lshlrev_b32_e32 v0, 2, v5
	s_lshl_b32 s2, s2, 7
	v_lshl_add_u64 v[30:31], s[6:7], 0, v[0:1]
	v_lshl_add_u64 v[32:33], s[44:45], 0, v[0:1]
	v_lshl_add_u64 v[34:35], s[46:47], 0, v[0:1]
	v_ashrrev_i32_e32 v3, 31, v2
	s_ashr_i32 s3, s2, 31
	v_and_b32_e32 v0, 15, v4
	v_add_u32_e32 v37, s2, v2
	v_lshl_add_u64 v[2:3], v[2:3], 0, s[2:3]
	v_lshlrev_b32_e32 v0, 4, v0
	v_mad_u64_u32 v[4:5], s[2:3], v2, s23, v[0:1]
	v_mad_i32_i24 v5, v3, s23, v5
	s_mov_b32 s78, 0
	v_lshl_add_u64 v[38:39], s[30:31], 0, v[4:5]
	s_barrier
	flat_load_dwordx4 v[138:141], v[24:25]
	flat_load_dwordx4 v[142:145], v[26:27]
	flat_load_dwordx4 v[146:149], v[32:33]
	flat_load_dwordx4 v[150:153], v[34:35]
	s_branch .LBB0_410

; DI f32x4 unpack4(u32x2 w) { return f32x4{bflo(w.x), bfhi(w.x), bflo(w.y), bfhi(w.y)}; }
; DI f32x4 shifted4(const Params& p, int l, int t, int col) {
;   const u16* z = (const u16*)(p.ws + WS_Z);
;   f32x4 cur = unpack4(*(const u32x2*)(z + (size_t)t * ZC + col));
;   f32x4 prv;
;   bool first;
;   int sb = 0;
;   if (t < TP) first = (t % LP) == 0;
;   else { int s = t - TP; sb = s >> 4; first = (s & 15) == 0; }
;   if (!first) prv = unpack4(*(const u32x2*)(z + (size_t)(t - 1) * ZC + col));
;   else if (t < TP) prv = f32x4{0.f, 0.f, 0.f, 0.f};
;   else prv = ld4(p.in[I_SSHIFT] + ((size_t)l * 32 + sb) * 2176 + col);
.LBB0_410:
	v_add_co_u32_e64 v2, s[38:39], -8, v38
	v_add_u32_e32 v8, s78, v37
	s_nop 0
	v_addc_co_u32_e64 v3, s[38:39], -1, v39, s[38:39]
	flat_load_dwordx2 v[40:41], v[2:3]
	flat_load_dwordx2 v[42:43], v[38:39]
	v_add_u32_e32 v0, 0xffff7f80, v8
	v_cmp_lt_i32_e64 s[38:39], s96, v8
	v_lshrrev_b32_e32 v0, 4, v0
	s_and_saveexec_b64 s[2:3], s[38:39]
	s_xor_b64 s[2:3], exec, s[2:3]
	v_mov_b64_e32 v[6:7], v[0:1]
	s_or_saveexec_b64 s[2:3], s[2:3]
	v_mul_hi_i32 v2, v8, s97
	v_lshrrev_b32_e32 v48, 31, v2
	v_ashrrev_i32_e32 v9, 11, v2
	v_mov_b32_e32 v2, v19
	s_xor_b64 exec, exec, s[2:3]
	v_add_u32_e32 v2, v9, v48
	v_mul_i32_i24_e32 v2, 0x1010, v2
	v_sub_u32_e32 v2, v8, v2
	v_mov_b64_e32 v[6:7], 0
	s_or_b64 exec, exec, s[2:3]
	v_cmp_ne_u32_e64 s[40:41], 0, v2
	v_add_u32_e32 v47, -1, v8
	v_mov_b32_e32 v156, v2
	s_and_saveexec_b64 s[2:3], s[40:41]
	s_xor_b64 s[2:3], exec, s[2:3]
	s_cbranch_execz .Lp2_first
	v_mad_i64_i32 v[2:3], s[8:9], v47, s23, v[20:21]
	flat_load_dwordx2 v[4:5], v[2:3]
	v_mad_i64_i32 v[154:155], s[8:9], v47, s23, v[28:29]
	flat_load_dwordx2 v[8:9], v[154:155]
.Lp2_first:
	s_andn2_saveexec_b64 s[2:3], s[2:3]
	s_cbranch_execz .Lp2_join
	v_mov_b32_e32 v5, 0
	v_mov_b32_e32 v4, 0
	v_mov_b32_e32 v3, 0
	v_mov_b32_e32 v2, 0
	v_mov_b32_e32 v9, 0
	v_mov_b32_e32 v8, 0
	s_and_saveexec_b64 s[8:9], s[38:39]
	s_cbranch_execz .Lp2_nos
	v_lshl_add_u64 v[2:3], v[6:7], 0, s[10:11]
	v_mad_u64_u32 v[4:5], s[40:41], v2, s54, v[22:23]
	v_mov_b32_e32 v2, v5
	v_mad_u64_u32 v[2:3], s[40:41], v3, s54, v[2:3]
	v_mov_b32_e32 v5, v2
	flat_load_dwordx4 v[2:5], v[4:5]
	v_lshl_add_u64 v[6:7], v[6:7], 0, s[10:11]
	v_mad_u64_u32 v[8:9], s[38:39], v6, s54, v[30:31]
	v_mov_b32_e32 v0, v9
	v_mad_u64_u32 v[6:7], s[38:39], v7, s54, v[0:1]
	v_mov_b32_e32 v9, v6
	flat_load_dwordx4 v[6:9], v[8:9]

; DI f32x4 unpack4(u32x2 w) { return f32x4{bflo(w.x), bfhi(w.x), bflo(w.y), bfhi(w.y)}; }
; DI float tanhf_(float x) { return 1.f - 2.f * __builtin_amdgcn_rcpf(__expf(2.f * x) + 1.f); }
; DI f32x4 shifted4(const Params& p, int l, int t, int col) {
;     ...
;   if (!first) prv = unpack4(*(const u32x2*)(z + (size_t)(t - 1) * ZC + col));
;   else if (t < TP) prv = f32x4{0.f, 0.f, 0.f, 0.f};
;   else prv = ld4(p.in[I_SSHIFT] + ((size_t)l * 32 + sb) * 2176 + col);
;   f32x4 m0 = ld4(p.in[I_MIX] + ((size_t)l * 2 + 0) * 2176 + col);
;   f32x4 m1 = ld4(p.in[I_MIX] + ((size_t)l * 2 + 1) * 2176 + col);
;   return cur * m0 + prv * m1;
; DI void rwkv_prep_tile(const int wv, const Params& p, int l, int mtile, int h, char* s0, char* s1, char* s2) {
;     ...
;       f32x4 a = shifted4(p, l, t0 + row, C_WL + c8);
;       f32x4 b = shifted4(p, l, t0 + row, C_WL + c8 + 4);
;       if (c8 < 64) {
; #pragma unroll
;         for (int e = 0; e < 4; ++e) { a[e] = tanhf_(a[e]); b[e] = tanhf_(b[e]); }
;       }
.Lp2_join:
	s_or_b64 exec, exec, s[2:3]
	s_waitcnt vmcnt(0) lgkmcnt(0)
	v_cmp_ne_u32_e64 s[40:41], 0, v156
	s_and_saveexec_b64 s[2:3], s[40:41]
	v_lshlrev_b32_e32 v2, 16, v4
	v_and_b32_e32 v3, 0xffff0000, v4
	v_lshlrev_b32_e32 v4, 16, v5
	v_and_b32_e32 v5, 0xffff0000, v5
	v_lshlrev_b32_e32 v6, 16, v8
	v_and_b32_e32 v7, 0xffff0000, v8
	v_lshlrev_b32_e32 v8, 16, v9
	v_and_b32_e32 v9, 0xffff0000, v9
	s_or_b64 exec, exec, s[2:3]
	v_lshlrev_b32_e32 v44, 16, v40
	v_and_b32_e32 v45, 0xffff0000, v40
	v_lshlrev_b32_e32 v40, 16, v41
	v_and_b32_e32 v41, 0xffff0000, v41
	v_pk_mul_f32 v[4:5], v[4:5], v[144:145]
	v_pk_mul_f32 v[14:15], v[2:3], v[142:143]
	v_pk_fma_f32 v[2:3], v[140:141], v[40:41], v[4:5]
	v_pk_fma_f32 v[4:5], v[138:139], v[44:45], v[14:15]
	v_lshlrev_b32_e32 v40, 16, v42
	v_and_b32_e32 v41, 0xffff0000, v42
	v_lshlrev_b32_e32 v42, 16, v43
	v_and_b32_e32 v43, 0xffff0000, v43
	v_mov_b32_e32 v0, 0x6000
	v_pk_mul_f32 v[8:9], v[8:9], v[152:153]
	v_pk_mul_f32 v[14:15], v[6:7], v[150:151]
	v_pk_fma_f32 v[6:7], v[148:149], v[42:43], v[8:9]
	v_pk_fma_f32 v[8:9], v[146:147], v[40:41], v[14:15]
	s_and_saveexec_b64 s[2:3], vcc
	s_cbranch_execz .LBB0_409
	v_add_f32_e32 v0, v4, v4
	v_add_f32_e32 v4, v8, v8
	v_add_f32_e32 v5, v5, v5
	v_mul_f32_e32 v4, 0x3fb8aa3b, v4
	v_mul_f32_e32 v5, 0x3fb8aa3b, v5
	v_exp_f32_e32 v4, v4
	v_exp_f32_e32 v5, v5
	v_mul_f32_e32 v0, 0x3fb8aa3b, v0
	v_add_f32_e32 v2, v2, v2
	v_add_f32_e32 v8, 1.0, v4
	v_add_f32_e32 v4, 1.0, v5
	v_add_f32_e32 v5, v9, v9
	v_mul_f32_e32 v5, 0x3fb8aa3b, v5
	v_exp_f32_e32 v5, v5
	v_add_f32_e32 v6, v6, v6
	v_add_f32_e32 v3, v3, v3
	v_exp_f32_e32 v0, v0
	v_add_f32_e32 v9, 1.0, v5
	v_add_f32_e32 v5, v7, v7
	v_mul_f32_e32 v2, 0x3fb8aa3b, v2
	v_mul_f32_e32 v6, 0x3fb8aa3b, v6
	v_mul_f32_e32 v3, 0x3fb8aa3b, v3
	v_mul_f32_e32 v5, 0x3fb8aa3b, v5
	v_exp_f32_e32 v2, v2
	v_exp_f32_e32 v6, v6
	v_exp_f32_e32 v3, v3
	v_exp_f32_e32 v7, v5
	v_add_f32_e32 v0, 1.0, v0
	v_add_f32_e32 v2, 1.0, v2
	v_add_f32_e32 v6, 1.0, v6
	v_add_f32_e32 v3, 1.0, v3
	v_rcp_f32_e64 v5, -v4
	v_rcp_f32_e64 v4, -v0
	v_add_f32_e32 v0, 1.0, v7
	v_rcp_f32_e64 v3, -v3
	v_rcp_f32_e64 v2, -v2
	v_rcp_f32_e64 v7, -v0
	v_rcp_f32_e64 v6, -v6
	v_rcp_f32_e64 v9, -v9
	v_rcp_f32_e64 v8, -v8
	v_pk_fma_f32 v[2:3], v[2:3], 2.0, 1.0 op_sel_hi:[1,0,0]
	v_pk_fma_f32 v[4:5], v[4:5], 2.0, 1.0 op_sel_hi:[1,0,0]
	v_pk_fma_f32 v[6:7], v[6:7], 2.0, 1.0 op_sel_hi:[1,0,0]
	v_pk_fma_f32 v[8:9], v[8:9], 2.0, 1.0 op_sel_hi:[1,0,0]
	v_mov_b32_e32 v0, 0
	s_branch .LBB0_409
